# P5 work queue: redundant loop-head barrier before the dequeue removed (the barrier after the dequeue and the items' own barriers remain); on top of the stacked version
# baseline (speedup 1.0000x reference)
; #define PH_BEGIN const int tid = otid(); const int G = gridDim.x; const int bid = osi((int)blockIdx.x); unsigned char* ws = osp(P.ws); float* out = osp(P.out); unsigned char* U = ws + WS_U; (void)tid; (void)G; (void)bid; (void)out; (void)U;
; __global__ void __launch_bounds__(512, 2) mega(Params P) {
;     ...
;             for (int rep = 0; rep < REP_P5; ++rep)
;             for (;;) {
;                 PH_BEGIN
;                 __syncthreads();
;                 if (tid == 0) *sitem = (int)atomicAdd(WSP(unsigned, WS_CTL) + 3600 + l + 2 * rep, 1u);
;                 __syncthreads();
;                 const int it = *sitem;
;                 if (it >= 1280) break;
.LBB0_889:
	s_mov_b32 s0, s21
	v_mbcnt_lo_u32_b32 v0, -1, 0
	v_mbcnt_hi_u32_b32 v0, -1, v0
	s_nop 0
	v_lshl_add_u32 v148, s0, 6, v0
	s_mov_b32 s0, s97
	v_cmp_eq_u32_e32 vcc, 0, v148
	v_readlane_b32 s0, v254, 19
	v_readlane_b32 s4, v254, 23
	v_readlane_b32 s5, v254, 24
	v_readlane_b32 s6, v254, 25
	v_readlane_b32 s7, v254, 26
	v_readlane_b32 s1, v254, 20
	s_mov_b64 s[52:53], s[6:7]
	s_mov_b64 s[16:17], s[4:5]
	v_readlane_b32 s2, v254, 21
	v_readlane_b32 s3, v254, 22
	s_and_saveexec_b64 s[0:1], vcc
	s_cbranch_execz .LBB0_893
	s_cmp_eq_u32 s98, 0
	s_cbranch_scc1 .Ldq_dyn
	s_mov_b32 s98, 0
	s_add_i32 s2, s97, 0xe0
	s_cmp_lt_u32 s97, 32
	s_cselect_b32 s2, s97, s2
	s_branch .Ldq_pub
